# attention A: final-pass gate loads issued at the unit loop top into v198-229 (copied in the final pass); on top of v86
# baseline (speedup 1.0000x reference)
; #define LAS __attribute__((address_space(3)))
; template <bool NT = false>
; __device__ __forceinline__ void final_store(const v4u (&gw)[8], LAS char* lds, bf16* yrow, int tid) {
; #pragma unroll
;     for (int it = 0; it < 8; ++it) {
;         const int tloc = (tid >> 3) + 64 * it, c = tid & 7;
;         const LAS char* row = lds + ACC_OFF + rho(tloc) * ACC_PITCH + 16 * c;
;         const v2u a0 = *(const LAS v2u*)row, a1 = *(const LAS v2u*)(row + 8);
;         const float inv = __builtin_amdgcn_rcpf(*((const LAS float*)(lds + LACC_OFF) + tloc));
;         v4u g = gw[it];
;         float gs[8];
;         { const unsigned gu[4] = {g.x, g.y, g.z, g.w};
; #pragma unroll
;           for (int k = 0; k < 4; ++k) { const float a = __builtin_bit_cast(float, gu[k] << 16), b = __builtin_bit_cast(float, gu[k] & 0xffff0000u);
;               gs[2 * k] = a * __builtin_amdgcn_rcpf(1.0f + __builtin_amdgcn_exp2f(-LOG2E * a)); gs[2 * k + 1] = b * __builtin_amdgcn_rcpf(1.0f + __builtin_amdgcn_exp2f(-LOG2E * b)); } }
;         v4u w;
;         w.x = cvtpk(__builtin_bit_cast(float, a0.x << 16) * inv * gs[0], __builtin_bit_cast(float, a0.x & 0xffff0000u) * inv * gs[1]);
;         w.y = cvtpk(__builtin_bit_cast(float, a0.y << 16) * inv * gs[2], __builtin_bit_cast(float, a0.y & 0xffff0000u) * inv * gs[3]);
;         w.z = cvtpk(__builtin_bit_cast(float, a1.x << 16) * inv * gs[4], __builtin_bit_cast(float, a1.x & 0xffff0000u) * inv * gs[5]);
;         w.w = cvtpk(__builtin_bit_cast(float, a1.y << 16) * inv * gs[6], __builtin_bit_cast(float, a1.y & 0xffff0000u) * inv * gs[7]);
;         if (NT) __builtin_nontemporal_store(w, (v4u*)(yrow + (size_t)tloc * 1024 + 8 * c)); else *(v4u*)(yrow + (size_t)tloc * 1024 + 8 * c) = w;
; __device__ __forceinline__ void attn_a_phase(Frame& F, const float cshift, const bf16* qkv, const bf16* gate, bf16* y, const float* t5, const float* qg, const float* kg) {
;     ...
;         const int s = u & 7, h = (u >> 3) & 15, bl = u >> 7;
;         const size_t tok0 = (size_t)bl * 4096 + 512 * s;
;         int tidf = tid; asm volatile("" : "+v"(tidf));
;         v4u gw[8]; gate_load(gw, gate + tok0 * 1024 + h * 64, tidf);
;         __syncthreads();
;         final_store<true>(gw, lds, y + tok0 * 1024 + h * 64, tidf);
.LBB0_312:
	s_or_b64 exec, exec, s[22:23]
	s_ashr_i32 s12, s15, 7
	s_ashr_i32 s13, s12, 31
	s_lshl_b32 s2, s15, 20
	s_lshl_b64 s[22:23], s[12:13], 23
	s_and_b32 s2, s2, 0x700000
	s_or_b32 s2, s22, s2
	s_add_u32 s12, s50, s2
	v_mov_b32_e32 v0, v158
	s_addc_u32 s13, s51, s23
	s_lshl_b32 s15, s15, 4
	s_and_b32 s15, s15, 0x780
	s_add_u32 s12, s12, s15
	v_ashrrev_i32_e32 v70, 3, v0
	v_lshlrev_b32_e32 v0, 4, v0
	s_addc_u32 s13, s13, 0
	v_and_b32_e32 v34, 0x70, v0
	v_mov_b32_e32 v35, v161
	v_ashrrev_i32_e32 v71, 31, v70
	v_lshl_add_u64 v[0:1], s[12:13], 0, v[34:35]
	v_lshlrev_b64 v[62:63], 11, v[70:71]
	v_lshl_add_u64 v[2:3], v[0:1], 0, v[62:63]
	v_add_u32_e32 v64, 64, v70
	v_ashrrev_i32_e32 v65, 31, v64
	v_lshlrev_b64 v[58:59], 11, v[64:65]
	v_lshl_add_u64 v[2:3], v[0:1], 0, v[58:59]
	v_add_u32_e32 v60, 0x80, v70
	v_ashrrev_i32_e32 v61, 31, v60
	v_add_u32_e32 v56, 0xc0, v70
	v_lshlrev_b64 v[54:55], 11, v[60:61]
	v_ashrrev_i32_e32 v57, 31, v56
	v_add_u32_e32 v52, 0x100, v70
	v_add_u32_e32 v38, 0x1c0, v70
	s_add_u32 s2, s16, s2
	v_lshl_add_u64 v[2:3], v[0:1], 0, v[54:55]
	v_lshlrev_b64 v[50:51], 11, v[56:57]
	v_ashrrev_i32_e32 v53, 31, v52
	v_add_u32_e32 v48, 0x140, v70
	v_ashrrev_i32_e32 v39, 31, v38
	s_addc_u32 s13, s17, s23
	v_lshl_add_u64 v[2:3], v[0:1], 0, v[50:51]
	v_lshlrev_b64 v[46:47], 11, v[52:53]
	v_ashrrev_i32_e32 v49, 31, v48
	v_add_u32_e32 v44, 0x180, v70
	v_lshlrev_b64 v[32:33], 11, v[38:39]
	s_add_u32 s12, s2, s15
	v_lshrrev_b32_e32 v39, 5, v70
	v_lshl_add_u64 v[2:3], v[0:1], 0, v[46:47]
	v_lshlrev_b64 v[42:43], 11, v[48:49]
	v_ashrrev_i32_e32 v45, 31, v44
	s_addc_u32 s13, s13, 0
	v_add_u32_e32 v40, 0, v34
	v_bitop3_b32 v39, v39, v70, 15 bitop3:0x6c
	v_lshl_add_u64 v[2:3], v[0:1], 0, v[42:43]
	v_lshlrev_b64 v[36:37], 11, v[44:45]
	v_lshl_add_u64 v[34:35], s[12:13], 0, v[34:35]
	v_mad_u64_u32 v[66:67], s[12:13], v39, s84, v[40:41]
	v_lshl_add_u32 v39, v70, 2, 0
	v_lshl_add_u64 v[2:3], v[0:1], 0, v[36:37]
	v_lshl_add_u64 v[0:1], v[0:1], 0, v[32:33]
	v_add_u32_e32 v39, 0x11000, v39
	v_lshl_add_u64 v[62:63], v[34:35], 0, v[62:63]
	s_waitcnt vmcnt(0) lgkmcnt(0)
	v_mov_b32_e32 v28, v198
	v_mov_b32_e32 v29, v199
	v_mov_b32_e32 v30, v200
	v_mov_b32_e32 v31, v201
	v_mov_b32_e32 v24, v202
	v_mov_b32_e32 v25, v203
	v_mov_b32_e32 v26, v204
	v_mov_b32_e32 v27, v205
	v_mov_b32_e32 v20, v206
	v_mov_b32_e32 v21, v207
	v_mov_b32_e32 v22, v208
	v_mov_b32_e32 v23, v209
	v_mov_b32_e32 v16, v210
	v_mov_b32_e32 v17, v211
	v_mov_b32_e32 v18, v212
	v_mov_b32_e32 v19, v213
	v_mov_b32_e32 v12, v214
	v_mov_b32_e32 v13, v215
	v_mov_b32_e32 v14, v216
	v_mov_b32_e32 v15, v217
	v_mov_b32_e32 v8, v218
	v_mov_b32_e32 v9, v219
	v_mov_b32_e32 v10, v220
	v_mov_b32_e32 v11, v221
	v_mov_b32_e32 v4, v222
	v_mov_b32_e32 v5, v223
	v_mov_b32_e32 v6, v224
	v_mov_b32_e32 v7, v225
	v_mov_b32_e32 v0, v226
	v_mov_b32_e32 v1, v227
	v_mov_b32_e32 v2, v228
	v_mov_b32_e32 v3, v229
	s_barrier
	ds_read2st64_b32 v[70:71], v39 offset1:1
	ds_read2_b64 v[66:69], v66 offset1:1
	s_addk_i32 s66, 0x1000
	s_cmp_eq_u32 s67, s59
	s_waitcnt lgkmcnt(1)
	v_rcp_f32_e32 v70, v70
	v_lshlrev_b32_e32 v72, 16, v28
	v_and_b32_e32 v73, 0xffff0000, v28
	v_mul_f32_e32 v28, 0xbfb8aa3b, v72
	v_exp_f32_e32 v28, v28
	v_and_b32_e32 v65, 0xffff0000, v24
	v_add_f32_e32 v28, 1.0, v28
	v_rcp_f32_e32 v74, v28
	v_mul_f32_e32 v28, 0xbfb8aa3b, v73
	v_exp_f32_e32 v28, v28
	s_nop 0
	v_add_f32_e32 v28, 1.0, v28
	v_rcp_f32_e32 v75, v28
	s_nop 0
	v_pk_mul_f32 v[72:73], v[74:75], v[72:73]
	s_waitcnt lgkmcnt(0)
	v_lshlrev_b32_e32 v74, 16, v66
	v_and_b32_e32 v75, 0xffff0000, v66
	v_pk_mul_f32 v[74:75], v[70:71], v[74:75] op_sel_hi:[0,1]
	v_pk_mul_f32 v[72:73], v[72:73], v[74:75]
	v_lshlrev_b32_e32 v66, 16, v67
	v_cvt_pk_bf16_f32 v28, v72, v73
	v_lshlrev_b32_e32 v72, 16, v29
	v_and_b32_e32 v73, 0xffff0000, v29
	v_mul_f32_e32 v29, 0xbfb8aa3b, v72
	v_exp_f32_e32 v29, v29
	v_and_b32_e32 v67, 0xffff0000, v67
	v_pk_mul_f32 v[66:67], v[70:71], v[66:67] op_sel_hi:[0,1]
	v_add_f32_e32 v29, 1.0, v29
	v_rcp_f32_e32 v74, v29
	v_mul_f32_e32 v29, 0xbfb8aa3b, v73
	v_exp_f32_e32 v29, v29
	s_nop 0
	v_add_f32_e32 v29, 1.0, v29
	v_rcp_f32_e32 v75, v29
	s_nop 0
	v_pk_mul_f32 v[72:73], v[74:75], v[72:73]
	s_nop 0
	v_pk_mul_f32 v[66:67], v[72:73], v[66:67]
	s_nop 0
	v_cvt_pk_bf16_f32 v29, v66, v67
	v_lshlrev_b32_e32 v66, 16, v30
	v_and_b32_e32 v67, 0xffff0000, v30
	v_mul_f32_e32 v30, 0xbfb8aa3b, v66
	v_exp_f32_e32 v30, v30
	s_nop 0
	v_add_f32_e32 v30, 1.0, v30
	v_rcp_f32_e32 v72, v30
	v_mul_f32_e32 v30, 0xbfb8aa3b, v67
	v_exp_f32_e32 v30, v30
	s_nop 0
	v_add_f32_e32 v30, 1.0, v30
	v_rcp_f32_e32 v73, v30
	s_nop 0
	v_pk_mul_f32 v[66:67], v[72:73], v[66:67]
	v_lshlrev_b32_e32 v72, 16, v68
	v_and_b32_e32 v73, 0xffff0000, v68
	v_pk_mul_f32 v[72:73], v[70:71], v[72:73] op_sel_hi:[0,1]
	v_pk_mul_f32 v[66:67], v[66:67], v[72:73]
	v_lshlrev_b32_e32 v68, 16, v69
	v_cvt_pk_bf16_f32 v30, v66, v67
	v_lshlrev_b32_e32 v66, 16, v31
	v_and_b32_e32 v67, 0xffff0000, v31
	v_mul_f32_e32 v31, 0xbfb8aa3b, v66
	v_exp_f32_e32 v31, v31
	v_and_b32_e32 v69, 0xffff0000, v69
	v_pk_mul_f32 v[68:69], v[70:71], v[68:69] op_sel_hi:[0,1]
	v_add_f32_e32 v31, 1.0, v31
	v_rcp_f32_e32 v72, v31
	v_mul_f32_e32 v31, 0xbfb8aa3b, v67
	v_exp_f32_e32 v31, v31
	s_nop 0
	v_add_f32_e32 v31, 1.0, v31
	v_rcp_f32_e32 v73, v31
	s_nop 0
	v_pk_mul_f32 v[66:67], v[72:73], v[66:67]
	s_nop 0
	v_pk_mul_f32 v[66:67], v[66:67], v[68:69]
	s_nop 0
	v_cvt_pk_bf16_f32 v31, v66, v67
	global_store_dwordx4 v[62:63], v[28:31], off nt
	v_rcp_f32_e32 v62, v71
	s_nop 0
	v_lshrrev_b32_e32 v28, 5, v64
	v_bitop3_b32 v28, v28, v64, 15 bitop3:0x6c
	v_lshlrev_b32_e32 v64, 16, v24
	v_mul_f32_e32 v24, 0xbfb8aa3b, v64
	v_exp_f32_e32 v24, v24
	v_mad_u64_u32 v[28:29], s[12:13], v28, s84, v[40:41]
	ds_read2_b64 v[28:31], v28 offset1:1
	v_add_f32_e32 v24, 1.0, v24
	v_rcp_f32_e32 v66, v24
	v_mul_f32_e32 v24, 0xbfb8aa3b, v65
	v_exp_f32_e32 v24, v24
	s_nop 0
	v_add_f32_e32 v24, 1.0, v24
	v_rcp_f32_e32 v67, v24
	s_nop 0
	v_pk_mul_f32 v[64:65], v[66:67], v[64:65]
	s_waitcnt lgkmcnt(0)
; #define LAS __attribute__((address_space(3)))
; __device__ __forceinline__ unsigned cvtpk(float lo, float hi) { f32x2_t v = {lo, hi}; bf16x2_t b = __builtin_convertvector(v, bf16x2_t); return __builtin_bit_cast(unsigned, b); }
; template <bool NT = false>
; __device__ __forceinline__ void final_store(const v4u (&gw)[8], LAS char* lds, bf16* yrow, int tid) {
;     ...
;     for (int it = 0; it < 8; ++it) {
;         const int tloc = (tid >> 3) + 64 * it, c = tid & 7;
;         const LAS char* row = lds + ACC_OFF + rho(tloc) * ACC_PITCH + 16 * c;
;         const v2u a0 = *(const LAS v2u*)row, a1 = *(const LAS v2u*)(row + 8);
;         const float inv = __builtin_amdgcn_rcpf(*((const LAS float*)(lds + LACC_OFF) + tloc));
;         v4u g = gw[it];
;         float gs[8];
;         { const unsigned gu[4] = {g.x, g.y, g.z, g.w};
; #pragma unroll
;           for (int k = 0; k < 4; ++k) { const float a = __builtin_bit_cast(float, gu[k] << 16), b = __builtin_bit_cast(float, gu[k] & 0xffff0000u);
;               gs[2 * k] = a * __builtin_amdgcn_rcpf(1.0f + __builtin_amdgcn_exp2f(-LOG2E * a)); gs[2 * k + 1] = b * __builtin_amdgcn_rcpf(1.0f + __builtin_amdgcn_exp2f(-LOG2E * b)); } }
;         v4u w;
;         w.x = cvtpk(__builtin_bit_cast(float, a0.x << 16) * inv * gs[0], __builtin_bit_cast(float, a0.x & 0xffff0000u) * inv * gs[1]);
;         w.y = cvtpk(__builtin_bit_cast(float, a0.y << 16) * inv * gs[2], __builtin_bit_cast(float, a0.y & 0xffff0000u) * inv * gs[3]);
;         w.z = cvtpk(__builtin_bit_cast(float, a1.x << 16) * inv * gs[4], __builtin_bit_cast(float, a1.x & 0xffff0000u) * inv * gs[5]);
;         w.w = cvtpk(__builtin_bit_cast(float, a1.y << 16) * inv * gs[6], __builtin_bit_cast(float, a1.y & 0xffff0000u) * inv * gs[7]);
;         if (NT) __builtin_nontemporal_store(w, (v4u*)(yrow + (size_t)tloc * 1024 + 8 * c)); else *(v4u*)(yrow + (size_t)tloc * 1024 + 8 * c) = w;
	v_lshlrev_b32_e32 v66, 16, v28
	v_and_b32_e32 v67, 0xffff0000, v28
	v_pk_mul_f32 v[66:67], v[62:63], v[66:67] op_sel_hi:[0,1]
	v_pk_mul_f32 v[64:65], v[64:65], v[66:67]
	v_lshlrev_b32_e32 v28, 16, v29
	v_cvt_pk_bf16_f32 v24, v64, v65
	v_lshlrev_b32_e32 v64, 16, v25
	v_and_b32_e32 v65, 0xffff0000, v25
	v_mul_f32_e32 v25, 0xbfb8aa3b, v64
	v_exp_f32_e32 v25, v25
	v_and_b32_e32 v29, 0xffff0000, v29
	v_pk_mul_f32 v[28:29], v[62:63], v[28:29] op_sel_hi:[0,1]
	v_add_f32_e32 v25, 1.0, v25
	v_rcp_f32_e32 v66, v25
	v_mul_f32_e32 v25, 0xbfb8aa3b, v65
	v_exp_f32_e32 v25, v25
	s_nop 0
	v_add_f32_e32 v25, 1.0, v25
	v_rcp_f32_e32 v67, v25
	s_nop 0
	v_pk_mul_f32 v[64:65], v[66:67], v[64:65]
	s_nop 0
	v_pk_mul_f32 v[28:29], v[64:65], v[28:29]
	s_nop 0
	v_cvt_pk_bf16_f32 v25, v28, v29
	v_lshlrev_b32_e32 v28, 16, v26
	v_and_b32_e32 v29, 0xffff0000, v26
	v_mul_f32_e32 v26, 0xbfb8aa3b, v28
	v_exp_f32_e32 v26, v26
	s_nop 0
	v_add_f32_e32 v26, 1.0, v26
	v_rcp_f32_e32 v64, v26
	v_mul_f32_e32 v26, 0xbfb8aa3b, v29
	v_exp_f32_e32 v26, v26
	s_nop 0
	v_add_f32_e32 v26, 1.0, v26
	v_rcp_f32_e32 v65, v26
	s_nop 0
	v_pk_mul_f32 v[28:29], v[64:65], v[28:29]
	v_lshlrev_b32_e32 v64, 16, v30
	v_and_b32_e32 v65, 0xffff0000, v30
	v_pk_mul_f32 v[64:65], v[62:63], v[64:65] op_sel_hi:[0,1]
	v_pk_mul_f32 v[28:29], v[28:29], v[64:65]
	v_lshlrev_b32_e32 v30, 16, v31
	v_cvt_pk_bf16_f32 v26, v28, v29
	v_lshlrev_b32_e32 v28, 16, v27
	v_and_b32_e32 v29, 0xffff0000, v27
	v_mul_f32_e32 v27, 0xbfb8aa3b, v28
	v_exp_f32_e32 v27, v27
	v_and_b32_e32 v31, 0xffff0000, v31
	v_pk_mul_f32 v[30:31], v[62:63], v[30:31] op_sel_hi:[0,1]
	v_add_f32_e32 v27, 1.0, v27
	v_rcp_f32_e32 v64, v27
	v_mul_f32_e32 v27, 0xbfb8aa3b, v29
	v_exp_f32_e32 v27, v27
	s_nop 0
	v_add_f32_e32 v27, 1.0, v27
	v_rcp_f32_e32 v65, v27
	s_nop 0
	v_pk_mul_f32 v[28:29], v[64:65], v[28:29]
	s_nop 0
	v_pk_mul_f32 v[28:29], v[28:29], v[30:31]
	v_lshlrev_b32_e32 v30, 16, v20
	v_and_b32_e32 v31, 0xffff0000, v20
	v_mul_f32_e32 v20, 0xbfb8aa3b, v30
	v_exp_f32_e32 v20, v20
	v_cvt_pk_bf16_f32 v27, v28, v29
	v_lshl_add_u64 v[28:29], v[34:35], 0, v[58:59]
	global_store_dwordx4 v[28:29], v[24:27], off nt
	v_add_f32_e32 v20, 1.0, v20
	v_rcp_f32_e32 v58, v20
	v_lshrrev_b32_e32 v24, 5, v60
	v_bitop3_b32 v24, v24, v60, 15 bitop3:0x6c
	v_mul_f32_e32 v20, 0xbfb8aa3b, v31
	v_mad_u64_u32 v[24:25], s[12:13], v24, s84, v[40:41]
	v_exp_f32_e32 v20, v20
	ds_read2_b64 v[24:27], v24 offset1:1
	ds_read2st64_b32 v[28:29], v39 offset0:2 offset1:3
	v_add_f32_e32 v20, 1.0, v20
	v_rcp_f32_e32 v59, v20
	s_waitcnt lgkmcnt(0)
	v_rcp_f32_e32 v28, v28
	v_pk_mul_f32 v[30:31], v[58:59], v[30:31]
	v_lshlrev_b32_e32 v58, 16, v24
	v_and_b32_e32 v59, 0xffff0000, v24
	v_pk_mul_f32 v[58:59], v[28:29], v[58:59] op_sel_hi:[0,1]
	v_pk_mul_f32 v[30:31], v[30:31], v[58:59]
	v_lshlrev_b32_e32 v24, 16, v25
	v_cvt_pk_bf16_f32 v20, v30, v31
	v_lshlrev_b32_e32 v30, 16, v21
	v_and_b32_e32 v31, 0xffff0000, v21
	v_mul_f32_e32 v21, 0xbfb8aa3b, v30
	v_exp_f32_e32 v21, v21
	v_and_b32_e32 v25, 0xffff0000, v25
	v_pk_mul_f32 v[24:25], v[28:29], v[24:25] op_sel_hi:[0,1]
	v_add_f32_e32 v21, 1.0, v21
	v_rcp_f32_e32 v58, v21
	v_mul_f32_e32 v21, 0xbfb8aa3b, v31
	v_exp_f32_e32 v21, v21
	s_nop 0
	v_add_f32_e32 v21, 1.0, v21
	v_rcp_f32_e32 v59, v21
	s_nop 0
	v_pk_mul_f32 v[30:31], v[58:59], v[30:31]
	s_nop 0
	v_pk_mul_f32 v[24:25], v[30:31], v[24:25]
	s_nop 0
	v_cvt_pk_bf16_f32 v21, v24, v25
	v_lshlrev_b32_e32 v24, 16, v22
	v_and_b32_e32 v25, 0xffff0000, v22
	v_mul_f32_e32 v22, 0xbfb8aa3b, v24
	v_exp_f32_e32 v22, v22
	s_nop 0
	v_add_f32_e32 v22, 1.0, v22
	v_rcp_f32_e32 v30, v22
	v_mul_f32_e32 v22, 0xbfb8aa3b, v25
	v_exp_f32_e32 v22, v22
	s_nop 0
	v_add_f32_e32 v22, 1.0, v22
	v_rcp_f32_e32 v31, v22
	s_nop 0
	v_pk_mul_f32 v[24:25], v[30:31], v[24:25]
	v_lshlrev_b32_e32 v30, 16, v26
	v_and_b32_e32 v31, 0xffff0000, v26
	v_pk_mul_f32 v[30:31], v[28:29], v[30:31] op_sel_hi:[0,1]
	v_pk_mul_f32 v[24:25], v[24:25], v[30:31]
	v_lshlrev_b32_e32 v26, 16, v27
	v_cvt_pk_bf16_f32 v22, v24, v25
	v_lshlrev_b32_e32 v24, 16, v23
	v_and_b32_e32 v25, 0xffff0000, v23
	v_mul_f32_e32 v23, 0xbfb8aa3b, v24
	v_exp_f32_e32 v23, v23
	v_and_b32_e32 v27, 0xffff0000, v27
	v_pk_mul_f32 v[26:27], v[28:29], v[26:27] op_sel_hi:[0,1]
	v_add_f32_e32 v23, 1.0, v23
	v_rcp_f32_e32 v30, v23
	v_mul_f32_e32 v23, 0xbfb8aa3b, v25
	v_exp_f32_e32 v23, v23
	s_nop 0
	v_add_f32_e32 v23, 1.0, v23
	v_rcp_f32_e32 v31, v23
	s_nop 0
	v_pk_mul_f32 v[24:25], v[30:31], v[24:25]
	s_nop 0
	v_pk_mul_f32 v[24:25], v[24:25], v[26:27]
	v_lshlrev_b32_e32 v26, 16, v16
	v_and_b32_e32 v27, 0xffff0000, v16
	v_mul_f32_e32 v16, 0xbfb8aa3b, v26
	v_exp_f32_e32 v16, v16
	v_cvt_pk_bf16_f32 v23, v24, v25
	v_lshl_add_u64 v[24:25], v[34:35], 0, v[54:55]
	global_store_dwordx4 v[24:25], v[20:23], off nt
	v_add_f32_e32 v16, 1.0, v16
	v_rcp_f32_e32 v28, v16
	v_mul_f32_e32 v16, 0xbfb8aa3b, v27
	v_exp_f32_e32 v16, v16
	v_lshrrev_b32_e32 v20, 5, v56
	v_bitop3_b32 v20, v20, v56, 15 bitop3:0x6c
	v_mad_u64_u32 v[20:21], s[12:13], v20, s84, v[40:41]
	ds_read2_b64 v[20:23], v20 offset1:1
	v_add_f32_e32 v16, 1.0, v16
	v_rcp_f32_e32 v24, v29
	v_rcp_f32_e32 v29, v16
	s_nop 0
	v_pk_mul_f32 v[26:27], v[28:29], v[26:27]
	s_waitcnt lgkmcnt(0)
; #define LAS __attribute__((address_space(3)))
; __device__ __forceinline__ unsigned cvtpk(float lo, float hi) { f32x2_t v = {lo, hi}; bf16x2_t b = __builtin_convertvector(v, bf16x2_t); return __builtin_bit_cast(unsigned, b); }
; template <bool NT = false>
; __device__ __forceinline__ void final_store(const v4u (&gw)[8], LAS char* lds, bf16* yrow, int tid) {
;     ...
;     for (int it = 0; it < 8; ++it) {
;         const int tloc = (tid >> 3) + 64 * it, c = tid & 7;
;         const LAS char* row = lds + ACC_OFF + rho(tloc) * ACC_PITCH + 16 * c;
;         const v2u a0 = *(const LAS v2u*)row, a1 = *(const LAS v2u*)(row + 8);
;         const float inv = __builtin_amdgcn_rcpf(*((const LAS float*)(lds + LACC_OFF) + tloc));
;         v4u g = gw[it];
;         float gs[8];
;         { const unsigned gu[4] = {g.x, g.y, g.z, g.w};
; #pragma unroll
;           for (int k = 0; k < 4; ++k) { const float a = __builtin_bit_cast(float, gu[k] << 16), b = __builtin_bit_cast(float, gu[k] & 0xffff0000u);
;               gs[2 * k] = a * __builtin_amdgcn_rcpf(1.0f + __builtin_amdgcn_exp2f(-LOG2E * a)); gs[2 * k + 1] = b * __builtin_amdgcn_rcpf(1.0f + __builtin_amdgcn_exp2f(-LOG2E * b)); } }
;         v4u w;
;         w.x = cvtpk(__builtin_bit_cast(float, a0.x << 16) * inv * gs[0], __builtin_bit_cast(float, a0.x & 0xffff0000u) * inv * gs[1]);
;         w.y = cvtpk(__builtin_bit_cast(float, a0.y << 16) * inv * gs[2], __builtin_bit_cast(float, a0.y & 0xffff0000u) * inv * gs[3]);
;         w.z = cvtpk(__builtin_bit_cast(float, a1.x << 16) * inv * gs[4], __builtin_bit_cast(float, a1.x & 0xffff0000u) * inv * gs[5]);
;         w.w = cvtpk(__builtin_bit_cast(float, a1.y << 16) * inv * gs[6], __builtin_bit_cast(float, a1.y & 0xffff0000u) * inv * gs[7]);
;         if (NT) __builtin_nontemporal_store(w, (v4u*)(yrow + (size_t)tloc * 1024 + 8 * c)); else *(v4u*)(yrow + (size_t)tloc * 1024 + 8 * c) = w;
	v_lshlrev_b32_e32 v28, 16, v20
	v_and_b32_e32 v29, 0xffff0000, v20
	v_pk_mul_f32 v[28:29], v[24:25], v[28:29] op_sel_hi:[0,1]
	v_pk_mul_f32 v[26:27], v[26:27], v[28:29]
	v_lshlrev_b32_e32 v20, 16, v21
	v_cvt_pk_bf16_f32 v16, v26, v27
	v_lshlrev_b32_e32 v26, 16, v17
	v_and_b32_e32 v27, 0xffff0000, v17
	v_mul_f32_e32 v17, 0xbfb8aa3b, v26
	v_exp_f32_e32 v17, v17
	v_and_b32_e32 v21, 0xffff0000, v21
	v_pk_mul_f32 v[20:21], v[24:25], v[20:21] op_sel_hi:[0,1]
	v_add_f32_e32 v17, 1.0, v17
	v_rcp_f32_e32 v28, v17
	v_mul_f32_e32 v17, 0xbfb8aa3b, v27
	v_exp_f32_e32 v17, v17
	s_nop 0
	v_add_f32_e32 v17, 1.0, v17
	v_rcp_f32_e32 v29, v17
	s_nop 0
	v_pk_mul_f32 v[26:27], v[28:29], v[26:27]
	s_nop 0
	v_pk_mul_f32 v[20:21], v[26:27], v[20:21]
	s_nop 0
	v_cvt_pk_bf16_f32 v17, v20, v21
	v_lshlrev_b32_e32 v20, 16, v18
	v_and_b32_e32 v21, 0xffff0000, v18
	v_mul_f32_e32 v18, 0xbfb8aa3b, v20
	v_exp_f32_e32 v18, v18
	s_nop 0
	v_add_f32_e32 v18, 1.0, v18
	v_rcp_f32_e32 v26, v18
	v_mul_f32_e32 v18, 0xbfb8aa3b, v21
	v_exp_f32_e32 v18, v18
	s_nop 0
	v_add_f32_e32 v18, 1.0, v18
	v_rcp_f32_e32 v27, v18
	s_nop 0
	v_pk_mul_f32 v[20:21], v[26:27], v[20:21]
	v_lshlrev_b32_e32 v26, 16, v22
	v_and_b32_e32 v27, 0xffff0000, v22
	v_pk_mul_f32 v[26:27], v[24:25], v[26:27] op_sel_hi:[0,1]
	v_pk_mul_f32 v[20:21], v[20:21], v[26:27]
	v_lshlrev_b32_e32 v22, 16, v23
	v_cvt_pk_bf16_f32 v18, v20, v21
	v_lshlrev_b32_e32 v20, 16, v19
	v_and_b32_e32 v21, 0xffff0000, v19
	v_mul_f32_e32 v19, 0xbfb8aa3b, v20
	v_exp_f32_e32 v19, v19
	v_and_b32_e32 v23, 0xffff0000, v23
	v_pk_mul_f32 v[22:23], v[24:25], v[22:23] op_sel_hi:[0,1]
	v_add_f32_e32 v19, 1.0, v19
	v_rcp_f32_e32 v26, v19
	v_mul_f32_e32 v19, 0xbfb8aa3b, v21
	v_exp_f32_e32 v19, v19
	s_nop 0
	v_add_f32_e32 v19, 1.0, v19
	v_rcp_f32_e32 v27, v19
	s_nop 0
	v_pk_mul_f32 v[20:21], v[26:27], v[20:21]
	s_nop 0
	v_pk_mul_f32 v[20:21], v[20:21], v[22:23]
	v_lshlrev_b32_e32 v22, 16, v12
	v_and_b32_e32 v23, 0xffff0000, v12
	v_mul_f32_e32 v12, 0xbfb8aa3b, v22
	v_exp_f32_e32 v12, v12
	v_cvt_pk_bf16_f32 v19, v20, v21
	v_lshl_add_u64 v[20:21], v[34:35], 0, v[50:51]
	global_store_dwordx4 v[20:21], v[16:19], off nt
	v_add_f32_e32 v12, 1.0, v12
	v_rcp_f32_e32 v24, v12
	v_lshrrev_b32_e32 v16, 5, v52
	v_bitop3_b32 v16, v16, v52, 15 bitop3:0x6c
	v_mul_f32_e32 v12, 0xbfb8aa3b, v23
	v_mad_u64_u32 v[16:17], s[12:13], v16, s84, v[40:41]
	v_exp_f32_e32 v12, v12
	ds_read2_b64 v[16:19], v16 offset1:1
	ds_read2st64_b32 v[20:21], v39 offset0:4 offset1:5
	v_add_f32_e32 v12, 1.0, v12
	v_rcp_f32_e32 v25, v12
	s_waitcnt lgkmcnt(0)
	v_rcp_f32_e32 v20, v20
	v_pk_mul_f32 v[22:23], v[24:25], v[22:23]
	v_lshlrev_b32_e32 v24, 16, v16
	v_and_b32_e32 v25, 0xffff0000, v16
	v_pk_mul_f32 v[24:25], v[20:21], v[24:25] op_sel_hi:[0,1]
	v_pk_mul_f32 v[22:23], v[22:23], v[24:25]
	v_lshlrev_b32_e32 v16, 16, v17
	v_cvt_pk_bf16_f32 v12, v22, v23
	v_lshlrev_b32_e32 v22, 16, v13
	v_and_b32_e32 v23, 0xffff0000, v13
	v_mul_f32_e32 v13, 0xbfb8aa3b, v22
	v_exp_f32_e32 v13, v13
	v_and_b32_e32 v17, 0xffff0000, v17
	v_pk_mul_f32 v[16:17], v[20:21], v[16:17] op_sel_hi:[0,1]
	v_add_f32_e32 v13, 1.0, v13
	v_rcp_f32_e32 v24, v13
	v_mul_f32_e32 v13, 0xbfb8aa3b, v23
	v_exp_f32_e32 v13, v13
	s_nop 0
	v_add_f32_e32 v13, 1.0, v13
	v_rcp_f32_e32 v25, v13
	s_nop 0
	v_pk_mul_f32 v[22:23], v[24:25], v[22:23]
	s_nop 0
	v_pk_mul_f32 v[16:17], v[22:23], v[16:17]
	s_nop 0
	v_cvt_pk_bf16_f32 v13, v16, v17
	v_lshlrev_b32_e32 v16, 16, v14
	v_and_b32_e32 v17, 0xffff0000, v14
	v_mul_f32_e32 v14, 0xbfb8aa3b, v16
	v_exp_f32_e32 v14, v14
	s_nop 0
	v_add_f32_e32 v14, 1.0, v14
	v_rcp_f32_e32 v22, v14
	v_mul_f32_e32 v14, 0xbfb8aa3b, v17
	v_exp_f32_e32 v14, v14
	s_nop 0
	v_add_f32_e32 v14, 1.0, v14
	v_rcp_f32_e32 v23, v14
	s_nop 0
	v_pk_mul_f32 v[16:17], v[22:23], v[16:17]
	v_lshlrev_b32_e32 v22, 16, v18
	v_and_b32_e32 v23, 0xffff0000, v18
	v_pk_mul_f32 v[22:23], v[20:21], v[22:23] op_sel_hi:[0,1]
	v_pk_mul_f32 v[16:17], v[16:17], v[22:23]
	v_lshlrev_b32_e32 v18, 16, v19
	v_cvt_pk_bf16_f32 v14, v16, v17
	v_lshlrev_b32_e32 v16, 16, v15
	v_and_b32_e32 v17, 0xffff0000, v15
	v_mul_f32_e32 v15, 0xbfb8aa3b, v16
	v_exp_f32_e32 v15, v15
	v_and_b32_e32 v19, 0xffff0000, v19
	v_pk_mul_f32 v[18:19], v[20:21], v[18:19] op_sel_hi:[0,1]
	v_add_f32_e32 v15, 1.0, v15
	v_rcp_f32_e32 v22, v15
	v_mul_f32_e32 v15, 0xbfb8aa3b, v17
	v_exp_f32_e32 v15, v15
	s_nop 0
	v_add_f32_e32 v15, 1.0, v15
	v_rcp_f32_e32 v23, v15
	s_nop 0
	v_pk_mul_f32 v[16:17], v[22:23], v[16:17]
	s_nop 0
	v_pk_mul_f32 v[16:17], v[16:17], v[18:19]
	v_lshlrev_b32_e32 v18, 16, v8
	v_and_b32_e32 v19, 0xffff0000, v8
	v_mul_f32_e32 v8, 0xbfb8aa3b, v18
	v_exp_f32_e32 v8, v8
	v_cvt_pk_bf16_f32 v15, v16, v17
	v_lshl_add_u64 v[16:17], v[34:35], 0, v[46:47]
	global_store_dwordx4 v[16:17], v[12:15], off nt
	v_add_f32_e32 v8, 1.0, v8
	v_rcp_f32_e32 v20, v8
	v_mul_f32_e32 v8, 0xbfb8aa3b, v19
	v_exp_f32_e32 v8, v8
	v_lshrrev_b32_e32 v12, 5, v48
	v_bitop3_b32 v12, v12, v48, 15 bitop3:0x6c
	v_mad_u64_u32 v[12:13], s[12:13], v12, s84, v[40:41]
	ds_read2_b64 v[12:15], v12 offset1:1
	v_add_f32_e32 v8, 1.0, v8
	v_rcp_f32_e32 v16, v21
	v_rcp_f32_e32 v21, v8
	s_nop 0
	v_pk_mul_f32 v[18:19], v[20:21], v[18:19]
	s_waitcnt lgkmcnt(0)
; #define LAS __attribute__((address_space(3)))
; __device__ __forceinline__ unsigned cvtpk(float lo, float hi) { f32x2_t v = {lo, hi}; bf16x2_t b = __builtin_convertvector(v, bf16x2_t); return __builtin_bit_cast(unsigned, b); }
; template <bool NT = false>
; __device__ __forceinline__ void final_store(const v4u (&gw)[8], LAS char* lds, bf16* yrow, int tid) {
;     ...
;     for (int it = 0; it < 8; ++it) {
;         const int tloc = (tid >> 3) + 64 * it, c = tid & 7;
;         const LAS char* row = lds + ACC_OFF + rho(tloc) * ACC_PITCH + 16 * c;
;         const v2u a0 = *(const LAS v2u*)row, a1 = *(const LAS v2u*)(row + 8);
;         const float inv = __builtin_amdgcn_rcpf(*((const LAS float*)(lds + LACC_OFF) + tloc));
;         v4u g = gw[it];
;         float gs[8];
;         { const unsigned gu[4] = {g.x, g.y, g.z, g.w};
; #pragma unroll
;           for (int k = 0; k < 4; ++k) { const float a = __builtin_bit_cast(float, gu[k] << 16), b = __builtin_bit_cast(float, gu[k] & 0xffff0000u);
;               gs[2 * k] = a * __builtin_amdgcn_rcpf(1.0f + __builtin_amdgcn_exp2f(-LOG2E * a)); gs[2 * k + 1] = b * __builtin_amdgcn_rcpf(1.0f + __builtin_amdgcn_exp2f(-LOG2E * b)); } }
;         v4u w;
;         w.x = cvtpk(__builtin_bit_cast(float, a0.x << 16) * inv * gs[0], __builtin_bit_cast(float, a0.x & 0xffff0000u) * inv * gs[1]);
;         w.y = cvtpk(__builtin_bit_cast(float, a0.y << 16) * inv * gs[2], __builtin_bit_cast(float, a0.y & 0xffff0000u) * inv * gs[3]);
;         w.z = cvtpk(__builtin_bit_cast(float, a1.x << 16) * inv * gs[4], __builtin_bit_cast(float, a1.x & 0xffff0000u) * inv * gs[5]);
;         w.w = cvtpk(__builtin_bit_cast(float, a1.y << 16) * inv * gs[6], __builtin_bit_cast(float, a1.y & 0xffff0000u) * inv * gs[7]);
;         if (NT) __builtin_nontemporal_store(w, (v4u*)(yrow + (size_t)tloc * 1024 + 8 * c)); else *(v4u*)(yrow + (size_t)tloc * 1024 + 8 * c) = w;
	v_lshlrev_b32_e32 v20, 16, v12
	v_and_b32_e32 v21, 0xffff0000, v12
	v_pk_mul_f32 v[20:21], v[16:17], v[20:21] op_sel_hi:[0,1]
	v_pk_mul_f32 v[18:19], v[18:19], v[20:21]
	v_lshlrev_b32_e32 v12, 16, v13
	v_cvt_pk_bf16_f32 v8, v18, v19
	v_lshlrev_b32_e32 v18, 16, v9
	v_and_b32_e32 v19, 0xffff0000, v9
	v_mul_f32_e32 v9, 0xbfb8aa3b, v18
	v_exp_f32_e32 v9, v9
	v_and_b32_e32 v13, 0xffff0000, v13
	v_pk_mul_f32 v[12:13], v[16:17], v[12:13] op_sel_hi:[0,1]
	v_add_f32_e32 v9, 1.0, v9
	v_rcp_f32_e32 v20, v9
	v_mul_f32_e32 v9, 0xbfb8aa3b, v19
	v_exp_f32_e32 v9, v9
	s_nop 0
	v_add_f32_e32 v9, 1.0, v9
	v_rcp_f32_e32 v21, v9
	s_nop 0
	v_pk_mul_f32 v[18:19], v[20:21], v[18:19]
	s_nop 0
	v_pk_mul_f32 v[12:13], v[18:19], v[12:13]
	s_nop 0
	v_cvt_pk_bf16_f32 v9, v12, v13
	v_lshlrev_b32_e32 v12, 16, v10
	v_and_b32_e32 v13, 0xffff0000, v10
	v_mul_f32_e32 v10, 0xbfb8aa3b, v12
	v_exp_f32_e32 v10, v10
	s_nop 0
	v_add_f32_e32 v10, 1.0, v10
	v_rcp_f32_e32 v18, v10
	v_mul_f32_e32 v10, 0xbfb8aa3b, v13
	v_exp_f32_e32 v10, v10
	s_nop 0
	v_add_f32_e32 v10, 1.0, v10
	v_rcp_f32_e32 v19, v10
	s_nop 0
	v_pk_mul_f32 v[12:13], v[18:19], v[12:13]
	v_lshlrev_b32_e32 v18, 16, v14
	v_and_b32_e32 v19, 0xffff0000, v14
	v_pk_mul_f32 v[18:19], v[16:17], v[18:19] op_sel_hi:[0,1]
	v_pk_mul_f32 v[12:13], v[12:13], v[18:19]
	v_lshlrev_b32_e32 v14, 16, v15
	v_cvt_pk_bf16_f32 v10, v12, v13
	v_lshlrev_b32_e32 v12, 16, v11
	v_and_b32_e32 v13, 0xffff0000, v11
	v_mul_f32_e32 v11, 0xbfb8aa3b, v12
	v_exp_f32_e32 v11, v11
	v_and_b32_e32 v15, 0xffff0000, v15
	v_pk_mul_f32 v[14:15], v[16:17], v[14:15] op_sel_hi:[0,1]
	v_add_f32_e32 v11, 1.0, v11
	v_rcp_f32_e32 v18, v11
	v_mul_f32_e32 v11, 0xbfb8aa3b, v13
	v_exp_f32_e32 v11, v11
	s_nop 0
	v_add_f32_e32 v11, 1.0, v11
	v_rcp_f32_e32 v19, v11
	s_nop 0
	v_pk_mul_f32 v[12:13], v[18:19], v[12:13]
	s_nop 0
	v_pk_mul_f32 v[12:13], v[12:13], v[14:15]
	v_lshlrev_b32_e32 v14, 16, v4
	v_and_b32_e32 v15, 0xffff0000, v4
	v_mul_f32_e32 v4, 0xbfb8aa3b, v14
	v_exp_f32_e32 v4, v4
	v_cvt_pk_bf16_f32 v11, v12, v13
	v_lshl_add_u64 v[12:13], v[34:35], 0, v[42:43]
	global_store_dwordx4 v[12:13], v[8:11], off nt
	v_add_f32_e32 v4, 1.0, v4
	v_rcp_f32_e32 v16, v4
	v_lshrrev_b32_e32 v8, 5, v44
	v_bitop3_b32 v8, v8, v44, 15 bitop3:0x6c
	v_mul_f32_e32 v4, 0xbfb8aa3b, v15
	v_mad_u64_u32 v[8:9], s[12:13], v8, s84, v[40:41]
	v_exp_f32_e32 v4, v4
	ds_read2_b64 v[8:11], v8 offset1:1
	ds_read2st64_b32 v[12:13], v39 offset0:6 offset1:7
	v_add_f32_e32 v4, 1.0, v4
	v_rcp_f32_e32 v17, v4
	s_waitcnt lgkmcnt(0)
	v_rcp_f32_e32 v12, v12
	v_pk_mul_f32 v[14:15], v[16:17], v[14:15]
	v_lshlrev_b32_e32 v16, 16, v8
	v_and_b32_e32 v17, 0xffff0000, v8
	v_pk_mul_f32 v[16:17], v[12:13], v[16:17] op_sel_hi:[0,1]
	v_pk_mul_f32 v[14:15], v[14:15], v[16:17]
	v_lshlrev_b32_e32 v8, 16, v9
	v_cvt_pk_bf16_f32 v4, v14, v15
	v_lshlrev_b32_e32 v14, 16, v5
	v_and_b32_e32 v15, 0xffff0000, v5
	v_mul_f32_e32 v5, 0xbfb8aa3b, v14
	v_exp_f32_e32 v5, v5
	v_and_b32_e32 v9, 0xffff0000, v9
	v_pk_mul_f32 v[8:9], v[12:13], v[8:9] op_sel_hi:[0,1]
	v_add_f32_e32 v5, 1.0, v5
	v_rcp_f32_e32 v16, v5
	v_mul_f32_e32 v5, 0xbfb8aa3b, v15
	v_exp_f32_e32 v5, v5
	s_nop 0
	v_add_f32_e32 v5, 1.0, v5
	v_rcp_f32_e32 v17, v5
	s_nop 0
	v_pk_mul_f32 v[14:15], v[16:17], v[14:15]
	s_nop 0
	v_pk_mul_f32 v[8:9], v[14:15], v[8:9]
	s_nop 0
	v_cvt_pk_bf16_f32 v5, v8, v9
	v_lshlrev_b32_e32 v8, 16, v6
	v_and_b32_e32 v9, 0xffff0000, v6
	v_mul_f32_e32 v6, 0xbfb8aa3b, v8
	v_exp_f32_e32 v6, v6
	s_nop 0
	v_add_f32_e32 v6, 1.0, v6
	v_rcp_f32_e32 v14, v6
	v_mul_f32_e32 v6, 0xbfb8aa3b, v9
	v_exp_f32_e32 v6, v6
	s_nop 0
	v_add_f32_e32 v6, 1.0, v6
	v_rcp_f32_e32 v15, v6
	s_nop 0
	v_pk_mul_f32 v[8:9], v[14:15], v[8:9]
	v_lshlrev_b32_e32 v14, 16, v10
	v_and_b32_e32 v15, 0xffff0000, v10
	v_pk_mul_f32 v[14:15], v[12:13], v[14:15] op_sel_hi:[0,1]
	v_pk_mul_f32 v[8:9], v[8:9], v[14:15]
	v_lshlrev_b32_e32 v10, 16, v11
	v_cvt_pk_bf16_f32 v6, v8, v9
	v_lshlrev_b32_e32 v8, 16, v7
	v_and_b32_e32 v9, 0xffff0000, v7
	v_mul_f32_e32 v7, 0xbfb8aa3b, v8
	v_exp_f32_e32 v7, v7
	v_and_b32_e32 v11, 0xffff0000, v11
	v_pk_mul_f32 v[10:11], v[12:13], v[10:11] op_sel_hi:[0,1]
	v_add_f32_e32 v7, 1.0, v7
	v_rcp_f32_e32 v14, v7
	v_mul_f32_e32 v7, 0xbfb8aa3b, v9
	v_exp_f32_e32 v7, v7
	s_nop 0
	v_add_f32_e32 v7, 1.0, v7
	v_rcp_f32_e32 v15, v7
	s_nop 0
	v_pk_mul_f32 v[8:9], v[14:15], v[8:9]
	s_nop 0
	v_pk_mul_f32 v[8:9], v[8:9], v[10:11]
	v_lshlrev_b32_e32 v10, 16, v0
	v_and_b32_e32 v11, 0xffff0000, v0
	v_mul_f32_e32 v0, 0xbfb8aa3b, v10
	v_exp_f32_e32 v0, v0
	v_cvt_pk_bf16_f32 v7, v8, v9
	v_lshl_add_u64 v[8:9], v[34:35], 0, v[36:37]
	global_store_dwordx4 v[8:9], v[4:7], off nt
	v_add_f32_e32 v0, 1.0, v0
	v_rcp_f32_e32 v12, v0
	v_mul_f32_e32 v0, 0xbfb8aa3b, v11
	v_exp_f32_e32 v0, v0
	v_lshrrev_b32_e32 v4, 5, v38
	v_bitop3_b32 v4, v4, v38, 15 bitop3:0x6c
	v_mad_u64_u32 v[4:5], s[12:13], v4, s84, v[40:41]
	ds_read2_b64 v[4:7], v4 offset1:1
	v_add_f32_e32 v0, 1.0, v0
	v_rcp_f32_e32 v8, v13
	v_rcp_f32_e32 v13, v0
	s_nop 0
	v_pk_mul_f32 v[10:11], v[12:13], v[10:11]
	s_waitcnt lgkmcnt(0)
	v_lshlrev_b32_e32 v12, 16, v4
	v_and_b32_e32 v13, 0xffff0000, v4
	v_pk_mul_f32 v[12:13], v[8:9], v[12:13] op_sel_hi:[0,1]
	v_pk_mul_f32 v[10:11], v[10:11], v[12:13]
	v_lshlrev_b32_e32 v4, 16, v5
	v_cvt_pk_bf16_f32 v0, v10, v11
	v_lshlrev_b32_e32 v10, 16, v1
	v_and_b32_e32 v11, 0xffff0000, v1
	v_mul_f32_e32 v1, 0xbfb8aa3b, v10
	v_exp_f32_e32 v1, v1
	v_and_b32_e32 v5, 0xffff0000, v5
	v_pk_mul_f32 v[4:5], v[8:9], v[4:5] op_sel_hi:[0,1]
	v_add_f32_e32 v1, 1.0, v1
	v_rcp_f32_e32 v12, v1
	v_mul_f32_e32 v1, 0xbfb8aa3b, v11
	v_exp_f32_e32 v1, v1
	s_nop 0
	v_add_f32_e32 v1, 1.0, v1
	v_rcp_f32_e32 v13, v1
	s_nop 0
	v_pk_mul_f32 v[10:11], v[12:13], v[10:11]
	s_nop 0
	v_pk_mul_f32 v[4:5], v[10:11], v[4:5]
	s_nop 0
	v_cvt_pk_bf16_f32 v1, v4, v5
	v_lshlrev_b32_e32 v4, 16, v2
	v_and_b32_e32 v5, 0xffff0000, v2
	v_mul_f32_e32 v2, 0xbfb8aa3b, v4
	v_exp_f32_e32 v2, v2
	s_nop 0
	v_add_f32_e32 v2, 1.0, v2
	v_rcp_f32_e32 v10, v2
	v_mul_f32_e32 v2, 0xbfb8aa3b, v5
	v_exp_f32_e32 v2, v2
	s_nop 0
	v_add_f32_e32 v2, 1.0, v2
	v_rcp_f32_e32 v11, v2
	s_nop 0
	v_pk_mul_f32 v[4:5], v[10:11], v[4:5]
	v_lshlrev_b32_e32 v10, 16, v6
	v_and_b32_e32 v11, 0xffff0000, v6
	v_pk_mul_f32 v[10:11], v[8:9], v[10:11] op_sel_hi:[0,1]
	v_pk_mul_f32 v[4:5], v[4:5], v[10:11]
	v_lshlrev_b32_e32 v6, 16, v7
	v_cvt_pk_bf16_f32 v2, v4, v5
	v_lshlrev_b32_e32 v4, 16, v3
	v_and_b32_e32 v5, 0xffff0000, v3
	v_mul_f32_e32 v3, 0xbfb8aa3b, v4
	v_exp_f32_e32 v3, v3
	v_and_b32_e32 v7, 0xffff0000, v7
	v_pk_mul_f32 v[6:7], v[8:9], v[6:7] op_sel_hi:[0,1]
	v_add_f32_e32 v3, 1.0, v3
	v_rcp_f32_e32 v10, v3
	v_mul_f32_e32 v3, 0xbfb8aa3b, v5
	v_exp_f32_e32 v3, v3
	s_nop 0
	v_add_f32_e32 v3, 1.0, v3
	v_rcp_f32_e32 v11, v3
	s_nop 0
	v_pk_mul_f32 v[4:5], v[10:11], v[4:5]
	s_nop 0
	v_pk_mul_f32 v[4:5], v[4:5], v[6:7]
	s_nop 0
	v_cvt_pk_bf16_f32 v3, v4, v5
	v_lshl_add_u64 v[4:5], v[34:35], 0, v[32:33]
	global_store_dwordx4 v[4:5], v[0:3], off nt
	s_cbranch_scc1 .LBB0_366
; __device__ __forceinline__ void gate_load(v4u (&gw)[8], const bf16* grow, int tid) {
; #pragma unroll
;     for (int it = 0; it < 8; ++it) gw[it] = *(const v4u*)(grow + (size_t)((tid >> 3) + 64 * it) * 1024 + 8 * (tid & 7));
; }
.LBB0_313:
	s_add_i32 s32, s67, s58
	s_ashr_i32 s100, s32, 7
	s_lshl_b32 s100, s100, 23
	s_lshl_b32 vcc_lo, s32, 20
	s_and_b32 vcc_lo, vcc_lo, 0x700000
	s_or_b32 s100, s100, vcc_lo
	s_lshl_b32 vcc_lo, s32, 4
	s_and_b32 vcc_lo, vcc_lo, 0x780
	s_add_u32 s100, s100, vcc_lo
	s_add_u32 vcc_lo, s50, s100
	s_addc_u32 vcc_hi, s51, 0
	v_and_b32_e32 v230, 7, v158
	v_lshlrev_b32_e32 v230, 4, v230
	v_lshrrev_b32_e32 v231, 3, v158
	v_lshl_add_u32 v230, v231, 11, v230
	global_load_dwordx4 v[198:201], v230, vcc
	v_add_u32_e32 v230, 0x20000, v230
	global_load_dwordx4 v[202:205], v230, vcc
	v_add_u32_e32 v230, 0x20000, v230
	global_load_dwordx4 v[206:209], v230, vcc
	v_add_u32_e32 v230, 0x20000, v230
	global_load_dwordx4 v[210:213], v230, vcc
	v_add_u32_e32 v230, 0x20000, v230
	global_load_dwordx4 v[214:217], v230, vcc
	v_add_u32_e32 v230, 0x20000, v230
	global_load_dwordx4 v[218:221], v230, vcc
	v_add_u32_e32 v230, 0x20000, v230
	global_load_dwordx4 v[222:225], v230, vcc
	v_add_u32_e32 v230, 0x20000, v230
	global_load_dwordx4 v[226:229], v230, vcc
	s_mov_b32 s2, s67
	s_add_i32 s15, s67, s58
	s_add_i32 s67, s67, 1
	s_cmp_ge_i32 s67, s59
	s_cselect_b64 s[22:23], -1, 0
	s_lshl_b32 s13, s15, 9
	s_and_b32 s42, s13, 0xe00
	s_ashr_i32 s13, s15, 3
	s_bfe_u32 s12, s15, 0x40003
	s_and_b32 s13, s13, -16
	s_or_b32 s12, s13, s12
	s_ashr_i32 s13, s12, 31
	s_lshl_b64 s[12:13], s[12:13], 19
	s_add_u32 s74, s46, s12
	s_addc_u32 s75, s47, s13
	s_lshl_b32 s12, s2, 12
	s_and_b32 s12, s12, 0x1000
	s_add_i32 s94, s1, s12
	s_add_i32 s12, s15, 1
	s_bfe_u32 s13, s12, 0x40003
	s_lshl_b32 s24, s12, 5
	s_and_b32 s25, s12, 7
	s_ashr_i32 s12, s12, 3
	s_and_b32 s24, s24, 0xe0
	s_sub_i32 s25, 2, s25
	s_and_b32 s12, s12, -16
	s_max_i32 s28, s25, 0
	s_xor_b32 s25, s24, 0xe0
	s_or_b32 s12, s12, s13
	s_lshr_b32 s25, s25, 5
	s_ashr_i32 s13, s12, 31
	s_min_u32 s29, s25, 2
	s_lshl_b64 s[12:13], s[12:13], 19
	s_add_u32 s12, s91, s12
	s_addc_u32 s13, s33, s13
	s_or_b32 s24, s24, s64
	s_lshl_b32 s30, s28, 5
	v_or_b32_e32 v0, s24, v159
	s_add_i32 s24, s24, s30
	s_sub_i32 s24, s24, 64
	v_ashrrev_i32_e32 v1, 31, v0
	s_ashr_i32 s25, s24, 31
	v_lshlrev_b64 v[0:1], 7, v[0:1]
	s_lshl_b64 s[24:25], s[24:25], 7
	v_lshl_add_u64 v[156:157], s[12:13], 0, v[0:1]
	s_add_u32 s12, s12, s24
	s_addc_u32 s13, s13, s25
	s_add_u32 s24, s12, 0x1000000
	s_addc_u32 s25, s13, 0
	s_add_u32 s26, s12, 0x2000000
	s_addc_u32 s27, s13, 0
	s_lshl_b32 s12, s67, 12
	s_and_b32 s12, s12, 0x1000
	s_sub_i32 s95, s29, s28
	s_add_i32 s12, s1, s12
	v_add_u32_e32 v0, s30, v167
	s_add_i32 s95, s95, 3
	s_sub_i32 s92, 4, s28
	v_lshl_add_u32 v183, v0, 2, s12
	s_cmp_lg_u32 s2, 0
	v_add_u32_e32 v184, 0xffffff80, v183
	s_cselect_b64 s[28:29], -1, 0
	s_mov_b32 s12, 0
	s_branch .LBB0_316
